# FFN-up SWIGLU epilogue stores marked sc0 sc1 (written through), leaving less dirty data for the grid barrier's L2 write-back
# baseline (speedup 1.0000x reference)
; DI float silu_f(float x) { return x * __builtin_amdgcn_rcpf(1.f + __expf(-x)); }
; template <int EPI, int MI>
; DI void gemm_tile(const GemmDesc& g, int tm, int tn, char* smem) {
;     ...
;   if (EPI == EPI_SWIGLU) {
;     u16* es = (u16*)smem;
; #pragma unroll
;     for (int mi = 0; mi < MI; ++mi)
; #pragma unroll
;       for (int i = 0; i < 16; ++i) {
;         const int lrow = wm * (32 * MI) + mi * 32 + (i & 3) + 8 * (i >> 2) + 4 * hh;
;         es[lrow * 64 + wn * 32 + r] = f2bf(silu_f(acc[mi][0][i]) * acc[mi][1][i]);
.LBB0_201:
	s_nop 7
	v_mul_f32_e32 v162, 0xbfb8aa3b, v80
	v_mul_f32_e32 v163, 0xbfb8aa3b, v81
	v_mul_f32_e32 v164, 0xbfb8aa3b, v82
	v_mul_f32_e32 v165, 0xbfb8aa3b, v83
	v_mul_f32_e32 v166, 0xbfb8aa3b, v84
	v_mul_f32_e32 v167, 0xbfb8aa3b, v85
	v_mul_f32_e32 v168, 0xbfb8aa3b, v86
	v_mul_f32_e32 v169, 0xbfb8aa3b, v87
	v_mul_f32_e32 v170, 0xbfb8aa3b, v88
	v_mul_f32_e32 v171, 0xbfb8aa3b, v89
	v_mul_f32_e32 v172, 0xbfb8aa3b, v90
	v_mul_f32_e32 v173, 0xbfb8aa3b, v91
	v_mul_f32_e32 v174, 0xbfb8aa3b, v92
	v_mul_f32_e32 v175, 0xbfb8aa3b, v93
	v_mul_f32_e32 v176, 0xbfb8aa3b, v94
	v_mul_f32_e32 v177, 0xbfb8aa3b, v95
	v_exp_f32_e32 v162, v162
	v_exp_f32_e32 v163, v163
	v_exp_f32_e32 v164, v164
	v_exp_f32_e32 v165, v165
	v_exp_f32_e32 v166, v166
	v_exp_f32_e32 v167, v167
	v_exp_f32_e32 v168, v168
	v_exp_f32_e32 v169, v169
	v_exp_f32_e32 v170, v170
	v_exp_f32_e32 v171, v171
	v_exp_f32_e32 v172, v172
	v_exp_f32_e32 v173, v173
	v_exp_f32_e32 v174, v174
	v_exp_f32_e32 v175, v175
	v_exp_f32_e32 v176, v176
	v_exp_f32_e32 v177, v177
	v_add_f32_e32 v162, 1.0, v162
	v_add_f32_e32 v163, 1.0, v163
	v_add_f32_e32 v164, 1.0, v164
	v_add_f32_e32 v165, 1.0, v165
	v_add_f32_e32 v166, 1.0, v166
	v_add_f32_e32 v167, 1.0, v167
	v_add_f32_e32 v168, 1.0, v168
	v_add_f32_e32 v169, 1.0, v169
	v_add_f32_e32 v170, 1.0, v170
	v_add_f32_e32 v171, 1.0, v171
	v_add_f32_e32 v172, 1.0, v172
	v_add_f32_e32 v173, 1.0, v173
	v_add_f32_e32 v174, 1.0, v174
	v_add_f32_e32 v175, 1.0, v175
	v_add_f32_e32 v176, 1.0, v176
	v_add_f32_e32 v177, 1.0, v177
	v_rcp_f32_e32 v162, v162
	v_rcp_f32_e32 v163, v163
	v_rcp_f32_e32 v164, v164
	v_rcp_f32_e32 v165, v165
	v_rcp_f32_e32 v166, v166
	v_rcp_f32_e32 v167, v167
	v_rcp_f32_e32 v168, v168
	v_rcp_f32_e32 v169, v169
	v_rcp_f32_e32 v170, v170
	v_rcp_f32_e32 v171, v171
	v_rcp_f32_e32 v172, v172
	v_rcp_f32_e32 v173, v173
	v_rcp_f32_e32 v174, v174
	v_rcp_f32_e32 v175, v175
	v_rcp_f32_e32 v176, v176
	v_rcp_f32_e32 v177, v177
	v_mul_f32_e32 v80, v80, v162
	v_mul_f32_e32 v81, v81, v163
	v_mul_f32_e32 v82, v82, v164
	v_mul_f32_e32 v83, v83, v165
	v_mul_f32_e32 v84, v84, v166
	v_mul_f32_e32 v85, v85, v167
	v_mul_f32_e32 v86, v86, v168
	v_mul_f32_e32 v87, v87, v169
	v_mul_f32_e32 v88, v88, v170
	v_mul_f32_e32 v89, v89, v171
	v_mul_f32_e32 v90, v90, v172
	v_mul_f32_e32 v91, v91, v173
	v_mul_f32_e32 v92, v92, v174
	v_mul_f32_e32 v93, v93, v175
	v_mul_f32_e32 v94, v94, v176
	v_mul_f32_e32 v95, v95, v177
	v_mul_f32_e32 v80, v64, v80
	v_mul_f32_e32 v81, v65, v81
	v_mul_f32_e32 v82, v66, v82
	v_mul_f32_e32 v83, v67, v83
	v_mul_f32_e32 v84, v68, v84
	v_mul_f32_e32 v85, v69, v85
	v_mul_f32_e32 v86, v70, v86
	v_mul_f32_e32 v87, v71, v87
	v_mul_f32_e32 v88, v72, v88
	v_mul_f32_e32 v89, v73, v89
	v_mul_f32_e32 v90, v74, v90
	v_mul_f32_e32 v91, v75, v91
	v_mul_f32_e32 v92, v76, v92
	v_mul_f32_e32 v93, v77, v93
	v_mul_f32_e32 v94, v78, v94
	v_mul_f32_e32 v95, v79, v95
	v_cvt_pk_bf16_f32 v80, v80, s0
	v_cvt_pk_bf16_f32 v81, v81, s0
	v_cvt_pk_bf16_f32 v82, v82, s0
	v_cvt_pk_bf16_f32 v83, v83, s0
	v_cvt_pk_bf16_f32 v84, v84, s0
	v_cvt_pk_bf16_f32 v85, v85, s0
	v_cvt_pk_bf16_f32 v86, v86, s0
	v_cvt_pk_bf16_f32 v87, v87, s0
	v_cvt_pk_bf16_f32 v88, v88, s0
	v_cvt_pk_bf16_f32 v89, v89, s0
	v_cvt_pk_bf16_f32 v90, v90, s0
	v_cvt_pk_bf16_f32 v91, v91, s0
	v_cvt_pk_bf16_f32 v92, v92, s0
	v_cvt_pk_bf16_f32 v93, v93, s0
	v_cvt_pk_bf16_f32 v94, v94, s0
	v_cvt_pk_bf16_f32 v95, v95, s0
	v_mul_f32_e32 v162, 0xbfb8aa3b, v48
	v_mul_f32_e32 v163, 0xbfb8aa3b, v49
	v_mul_f32_e32 v164, 0xbfb8aa3b, v50
	v_mul_f32_e32 v165, 0xbfb8aa3b, v51
	v_mul_f32_e32 v166, 0xbfb8aa3b, v52
	v_mul_f32_e32 v167, 0xbfb8aa3b, v53
	v_mul_f32_e32 v168, 0xbfb8aa3b, v54
	v_mul_f32_e32 v169, 0xbfb8aa3b, v55
	v_mul_f32_e32 v170, 0xbfb8aa3b, v56
	v_mul_f32_e32 v171, 0xbfb8aa3b, v57
	v_mul_f32_e32 v172, 0xbfb8aa3b, v58
	v_mul_f32_e32 v173, 0xbfb8aa3b, v59
	v_mul_f32_e32 v174, 0xbfb8aa3b, v60
	v_mul_f32_e32 v175, 0xbfb8aa3b, v61
	v_mul_f32_e32 v176, 0xbfb8aa3b, v62
	v_mul_f32_e32 v177, 0xbfb8aa3b, v63
	v_exp_f32_e32 v162, v162
	v_exp_f32_e32 v163, v163
	v_exp_f32_e32 v164, v164
	v_exp_f32_e32 v165, v165
	v_exp_f32_e32 v166, v166
	v_exp_f32_e32 v167, v167
	v_exp_f32_e32 v168, v168
	v_exp_f32_e32 v169, v169
	v_exp_f32_e32 v170, v170
	v_exp_f32_e32 v171, v171
	v_exp_f32_e32 v172, v172
	v_exp_f32_e32 v173, v173
	v_exp_f32_e32 v174, v174
	v_exp_f32_e32 v175, v175
	v_exp_f32_e32 v176, v176
	v_exp_f32_e32 v177, v177
	v_add_f32_e32 v162, 1.0, v162
	v_add_f32_e32 v163, 1.0, v163
	v_add_f32_e32 v164, 1.0, v164
	v_add_f32_e32 v165, 1.0, v165
	v_add_f32_e32 v166, 1.0, v166
	v_add_f32_e32 v167, 1.0, v167
	v_add_f32_e32 v168, 1.0, v168
	v_add_f32_e32 v169, 1.0, v169
	v_add_f32_e32 v170, 1.0, v170
	v_add_f32_e32 v171, 1.0, v171
	v_add_f32_e32 v172, 1.0, v172
	v_add_f32_e32 v173, 1.0, v173
	v_add_f32_e32 v174, 1.0, v174
	v_add_f32_e32 v175, 1.0, v175
	v_add_f32_e32 v176, 1.0, v176
	v_add_f32_e32 v177, 1.0, v177
	v_rcp_f32_e32 v162, v162
	v_rcp_f32_e32 v163, v163
	v_rcp_f32_e32 v164, v164
	v_rcp_f32_e32 v165, v165
	v_rcp_f32_e32 v166, v166
	v_rcp_f32_e32 v167, v167
	v_rcp_f32_e32 v168, v168
	v_rcp_f32_e32 v169, v169
	v_rcp_f32_e32 v170, v170
	v_rcp_f32_e32 v171, v171
	v_rcp_f32_e32 v172, v172
	v_rcp_f32_e32 v173, v173
	v_rcp_f32_e32 v174, v174
	v_rcp_f32_e32 v175, v175
	v_rcp_f32_e32 v176, v176
	v_rcp_f32_e32 v177, v177
	v_mul_f32_e32 v48, v48, v162
	v_mul_f32_e32 v49, v49, v163
	v_mul_f32_e32 v50, v50, v164
	v_mul_f32_e32 v51, v51, v165
	v_mul_f32_e32 v52, v52, v166
	v_mul_f32_e32 v53, v53, v167
	v_mul_f32_e32 v54, v54, v168
	v_mul_f32_e32 v55, v55, v169
	v_mul_f32_e32 v56, v56, v170
	v_mul_f32_e32 v57, v57, v171
	v_mul_f32_e32 v58, v58, v172
; DI float silu_f(float x) { return x * __builtin_amdgcn_rcpf(1.f + __expf(-x)); }
; template <int EPI, int MI>
; DI void gemm_tile(const GemmDesc& g, int tm, int tn, char* smem) {
;     ...
; #pragma unroll
;     for (int mi = 0; mi < MI; ++mi)
; #pragma unroll
;       for (int i = 0; i < 16; ++i) {
;         const int lrow = wm * (32 * MI) + mi * 32 + (i & 3) + 8 * (i >> 2) + 4 * hh;
;         es[lrow * 64 + wn * 32 + r] = f2bf(silu_f(acc[mi][0][i]) * acc[mi][1][i]);
;       }
;     __syncthreads();
	v_mul_f32_e32 v59, v59, v173
	v_mul_f32_e32 v60, v60, v174
	v_mul_f32_e32 v61, v61, v175
	v_mul_f32_e32 v62, v62, v176
	v_mul_f32_e32 v63, v63, v177
	v_mul_f32_e32 v48, v32, v48
	v_mul_f32_e32 v49, v33, v49
	v_mul_f32_e32 v50, v34, v50
	v_mul_f32_e32 v51, v35, v51
	v_mul_f32_e32 v52, v36, v52
	v_mul_f32_e32 v53, v37, v53
	v_mul_f32_e32 v54, v38, v54
	v_mul_f32_e32 v55, v39, v55
	v_mul_f32_e32 v56, v40, v56
	v_mul_f32_e32 v57, v41, v57
	v_mul_f32_e32 v58, v42, v58
	v_mul_f32_e32 v59, v43, v59
	v_mul_f32_e32 v60, v44, v60
	v_mul_f32_e32 v61, v45, v61
	v_mul_f32_e32 v62, v46, v62
	v_mul_f32_e32 v63, v47, v63
	v_cvt_pk_bf16_f32 v48, v48, s0
	v_cvt_pk_bf16_f32 v49, v49, s0
	v_cvt_pk_bf16_f32 v50, v50, s0
	v_cvt_pk_bf16_f32 v51, v51, s0
	v_cvt_pk_bf16_f32 v52, v52, s0
	v_cvt_pk_bf16_f32 v53, v53, s0
	v_cvt_pk_bf16_f32 v54, v54, s0
	v_cvt_pk_bf16_f32 v55, v55, s0
	v_cvt_pk_bf16_f32 v56, v56, s0
	v_cvt_pk_bf16_f32 v57, v57, s0
	v_cvt_pk_bf16_f32 v58, v58, s0
	v_cvt_pk_bf16_f32 v59, v59, s0
	v_cvt_pk_bf16_f32 v60, v60, s0
	v_cvt_pk_bf16_f32 v61, v61, s0
	v_cvt_pk_bf16_f32 v62, v62, s0
	v_cvt_pk_bf16_f32 v63, v63, s0
	v_mul_f32_e32 v162, 0xbfb8aa3b, v16
	v_mul_f32_e32 v163, 0xbfb8aa3b, v17
	v_mul_f32_e32 v164, 0xbfb8aa3b, v18
	v_mul_f32_e32 v165, 0xbfb8aa3b, v19
	v_mul_f32_e32 v166, 0xbfb8aa3b, v20
	v_mul_f32_e32 v167, 0xbfb8aa3b, v21
	v_mul_f32_e32 v168, 0xbfb8aa3b, v22
	v_mul_f32_e32 v169, 0xbfb8aa3b, v23
	v_mul_f32_e32 v170, 0xbfb8aa3b, v24
	v_mul_f32_e32 v171, 0xbfb8aa3b, v25
	v_mul_f32_e32 v172, 0xbfb8aa3b, v26
	v_mul_f32_e32 v173, 0xbfb8aa3b, v27
	v_mul_f32_e32 v174, 0xbfb8aa3b, v28
	v_mul_f32_e32 v175, 0xbfb8aa3b, v29
	v_mul_f32_e32 v176, 0xbfb8aa3b, v30
	v_mul_f32_e32 v177, 0xbfb8aa3b, v31
	v_exp_f32_e32 v162, v162
	v_exp_f32_e32 v163, v163
	v_exp_f32_e32 v164, v164
	v_exp_f32_e32 v165, v165
	v_exp_f32_e32 v166, v166
	v_exp_f32_e32 v167, v167
	v_exp_f32_e32 v168, v168
	v_exp_f32_e32 v169, v169
	v_exp_f32_e32 v170, v170
	v_exp_f32_e32 v171, v171
	v_exp_f32_e32 v172, v172
	v_exp_f32_e32 v173, v173
	v_exp_f32_e32 v174, v174
	v_exp_f32_e32 v175, v175
	v_exp_f32_e32 v176, v176
	v_exp_f32_e32 v177, v177
	v_add_f32_e32 v162, 1.0, v162
	v_add_f32_e32 v163, 1.0, v163
	v_add_f32_e32 v164, 1.0, v164
	v_add_f32_e32 v165, 1.0, v165
	v_add_f32_e32 v166, 1.0, v166
	v_add_f32_e32 v167, 1.0, v167
	v_add_f32_e32 v168, 1.0, v168
	v_add_f32_e32 v169, 1.0, v169
	v_add_f32_e32 v170, 1.0, v170
	v_add_f32_e32 v171, 1.0, v171
	v_add_f32_e32 v172, 1.0, v172
	v_add_f32_e32 v173, 1.0, v173
	v_add_f32_e32 v174, 1.0, v174
	v_add_f32_e32 v175, 1.0, v175
	v_add_f32_e32 v176, 1.0, v176
	v_add_f32_e32 v177, 1.0, v177
	v_rcp_f32_e32 v162, v162
	v_rcp_f32_e32 v163, v163
	v_rcp_f32_e32 v164, v164
	v_rcp_f32_e32 v165, v165
	v_rcp_f32_e32 v166, v166
	v_rcp_f32_e32 v167, v167
	v_rcp_f32_e32 v168, v168
	v_rcp_f32_e32 v169, v169
	v_rcp_f32_e32 v170, v170
	v_rcp_f32_e32 v171, v171
	v_rcp_f32_e32 v172, v172
	v_rcp_f32_e32 v173, v173
	v_rcp_f32_e32 v174, v174
	v_rcp_f32_e32 v175, v175
	v_rcp_f32_e32 v176, v176
	v_rcp_f32_e32 v177, v177
	v_mul_f32_e32 v16, v16, v162
	v_mul_f32_e32 v17, v17, v163
	v_mul_f32_e32 v18, v18, v164
	v_mul_f32_e32 v19, v19, v165
	v_mul_f32_e32 v20, v20, v166
	v_mul_f32_e32 v21, v21, v167
	v_mul_f32_e32 v22, v22, v168
	v_mul_f32_e32 v23, v23, v169
	v_mul_f32_e32 v24, v24, v170
	v_mul_f32_e32 v25, v25, v171
	v_mul_f32_e32 v26, v26, v172
	v_mul_f32_e32 v27, v27, v173
	v_mul_f32_e32 v28, v28, v174
	v_mul_f32_e32 v29, v29, v175
	v_mul_f32_e32 v30, v30, v176
	v_mul_f32_e32 v31, v31, v177
	v_mul_f32_e32 v16, v0, v16
	v_mul_f32_e32 v17, v1, v17
	v_mul_f32_e32 v18, v2, v18
	v_mul_f32_e32 v19, v3, v19
	v_mul_f32_e32 v20, v4, v20
	v_mul_f32_e32 v21, v5, v21
	v_mul_f32_e32 v22, v6, v22
	v_mul_f32_e32 v23, v7, v23
	v_mul_f32_e32 v24, v8, v24
	v_mul_f32_e32 v25, v9, v25
	v_mul_f32_e32 v26, v10, v26
	v_mul_f32_e32 v27, v11, v27
	v_mul_f32_e32 v28, v12, v28
	v_mul_f32_e32 v29, v13, v29
	v_mul_f32_e32 v30, v14, v30
	v_mul_f32_e32 v31, v15, v31
	v_cvt_pk_bf16_f32 v16, v16, s0
	v_cvt_pk_bf16_f32 v17, v17, s0
	v_cvt_pk_bf16_f32 v18, v18, s0
	v_cvt_pk_bf16_f32 v19, v19, s0
	v_cvt_pk_bf16_f32 v20, v20, s0
	v_cvt_pk_bf16_f32 v21, v21, s0
	v_cvt_pk_bf16_f32 v22, v22, s0
	v_cvt_pk_bf16_f32 v23, v23, s0
	v_cvt_pk_bf16_f32 v24, v24, s0
	v_cvt_pk_bf16_f32 v25, v25, s0
	v_cvt_pk_bf16_f32 v26, v26, s0
	v_cvt_pk_bf16_f32 v27, v27, s0
	v_cvt_pk_bf16_f32 v28, v28, s0
	v_cvt_pk_bf16_f32 v29, v29, s0
	v_cvt_pk_bf16_f32 v30, v30, s0
	v_cvt_pk_bf16_f32 v31, v31, s0
	v_lshlrev_b32_e32 v99, 9, v122
	v_lshlrev_b32_e32 v100, 6, v123
	v_add3_u32 v99, 0, v99, v100
	v_lshlrev_b32_e32 v100, 1, v121
	v_readlane_b32 s16, v221, 5
	v_readlane_b32 s17, v221, 6
	s_movk_i32 s0, 0x3000
	v_mul_lo_u32 v64, v120, s0
	v_add3_u32 v64, v99, v100, v64
	s_movk_i32 s15, 0x1600
	v_lshlrev_b32_e32 v4, 4, v115
	v_mov_b32_e32 v5, v96
	v_mov_b64_e32 v[6:7], s[16:17]
	v_mad_i64_i32 v[8:9], s[16:17], v98, s15, v[6:7]
	v_add_u32_e32 v10, 0, v4
	v_lshl_add_u32 v0, v97, 7, v10
	ds_write_b16 v64, v80
	ds_write_b16 v64, v81 offset:128
	ds_write_b16 v64, v82 offset:256
	ds_write_b16 v64, v83 offset:384
	ds_write_b16 v64, v84 offset:1024
	ds_write_b16 v64, v85 offset:1152
	ds_write_b16 v64, v86 offset:1280
	ds_write_b16 v64, v87 offset:1408
	ds_write_b16 v64, v88 offset:2048
	ds_write_b16 v64, v89 offset:2176
	ds_write_b16 v64, v90 offset:2304
	ds_write_b16 v64, v91 offset:2432
	ds_write_b16 v64, v92 offset:3072
	ds_write_b16 v64, v93 offset:3200
	ds_write_b16 v64, v94 offset:3328
	ds_write_b16 v64, v95 offset:3456
	ds_write_b16 v64, v48 offset:4096
	ds_write_b16 v64, v49 offset:4224
	ds_write_b16 v64, v50 offset:4352
	ds_write_b16 v64, v51 offset:4480
	ds_write_b16 v64, v52 offset:5120
	ds_write_b16 v64, v53 offset:5248
	ds_write_b16 v64, v54 offset:5376
	ds_write_b16 v64, v55 offset:5504
	ds_write_b16 v64, v56 offset:6144
	ds_write_b16 v64, v57 offset:6272
	ds_write_b16 v64, v58 offset:6400
	ds_write_b16 v64, v59 offset:6528
	ds_write_b16 v64, v60 offset:7168
	ds_write_b16 v64, v61 offset:7296
	ds_write_b16 v64, v62 offset:7424
	ds_write_b16 v64, v63 offset:7552
	ds_write_b16 v64, v16 offset:8192
	ds_write_b16 v64, v17 offset:8320
	ds_write_b16 v64, v18 offset:8448
	ds_write_b16 v64, v19 offset:8576
	ds_write_b16 v64, v20 offset:9216
	ds_write_b16 v64, v21 offset:9344
	ds_write_b16 v64, v22 offset:9472
	ds_write_b16 v64, v23 offset:9600
	ds_write_b16 v64, v24 offset:10240
	ds_write_b16 v64, v25 offset:10368
	ds_write_b16 v64, v26 offset:10496
	ds_write_b16 v64, v27 offset:10624
	ds_write_b16 v64, v28 offset:11264
	ds_write_b16 v64, v29 offset:11392
	ds_write_b16 v64, v30 offset:11520
	ds_write_b16 v64, v31 offset:11648
	s_waitcnt lgkmcnt(0)
	s_barrier
; template <int EPI, int MI>
; DI void gemm_tile(const GemmDesc& g, int tm, int tn, char* smem) {
;     ...
; #pragma unroll
;     for (int j = 0; j < 2 * MI; ++j) {
;       const int lrow = (tid >> 3) + 32 * j, ch = tid & 7;
;       const u32x4 v = *(const u32x4*)(es + lrow * 64 + ch * 8);
;       *(u32x4*)(g.o16 + (size_t)(m0 + lrow) * g.ldo + (n0 >> 1) + ch * 8) = v;
;     }
;     __syncthreads();
; template <int EPI, int MI>
; DI void gemm_phase(const GemmDesc& g, char* smem, int vb, int nvb) {
;     ...
;   for (int q = start; q < local; q += step) {
	s_lshl_b32 s0, s39, 6
	ds_read_b128 v[0:3], v0
	s_ashr_i32 s1, s0, 31
	s_lshl_b64 s[0:1], s[0:1], 1
	v_lshl_add_u64 v[8:9], v[8:9], 0, s[0:1]
	v_lshl_add_u64 v[8:9], v[8:9], 0, v[4:5]
	s_waitcnt lgkmcnt(0)
	global_store_dwordx4 v[8:9], v[0:3], off sc0 sc1
	v_add_u32_e32 v8, 32, v97
	s_nop 0
	v_lshl_add_u32 v0, v8, 7, v10
	ds_read_b128 v[0:3], v0
	v_add_u32_e32 v8, s38, v8
	v_mad_i64_i32 v[8:9], s[16:17], v8, s15, v[6:7]
	v_lshl_add_u64 v[8:9], v[8:9], 0, s[0:1]
	v_lshl_add_u64 v[8:9], v[8:9], 0, v[4:5]
	s_waitcnt lgkmcnt(0)
	global_store_dwordx4 v[8:9], v[0:3], off sc0 sc1
	v_add_u32_e32 v8, 64, v97
	s_nop 0
	v_lshl_add_u32 v0, v8, 7, v10
	ds_read_b128 v[0:3], v0
	v_add_u32_e32 v8, s38, v8
	v_mad_i64_i32 v[8:9], s[16:17], v8, s15, v[6:7]
	v_lshl_add_u64 v[8:9], v[8:9], 0, s[0:1]
	v_lshl_add_u64 v[8:9], v[8:9], 0, v[4:5]
	s_waitcnt lgkmcnt(0)
	global_store_dwordx4 v[8:9], v[0:3], off sc0 sc1
	v_add_u32_e32 v8, 0x60, v97
	s_nop 0
	v_lshl_add_u32 v0, v8, 7, v10
	ds_read_b128 v[0:3], v0
	v_add_u32_e32 v8, s38, v8
	v_mad_i64_i32 v[8:9], s[16:17], v8, s15, v[6:7]
	v_lshl_add_u64 v[8:9], v[8:9], 0, s[0:1]
	v_lshl_add_u64 v[8:9], v[8:9], 0, v[4:5]
	s_waitcnt lgkmcnt(0)
	global_store_dwordx4 v[8:9], v[0:3], off sc0 sc1
	v_add_u32_e32 v8, 0x80, v97
	s_nop 0
	v_lshl_add_u32 v0, v8, 7, v10
	ds_read_b128 v[0:3], v0
	v_add_u32_e32 v8, s38, v8
	v_mad_i64_i32 v[8:9], s[16:17], v8, s15, v[6:7]
	v_lshl_add_u64 v[8:9], v[8:9], 0, s[0:1]
	v_lshl_add_u64 v[8:9], v[8:9], 0, v[4:5]
	s_waitcnt lgkmcnt(0)
	global_store_dwordx4 v[8:9], v[0:3], off sc0 sc1
	v_add_u32_e32 v8, 0xa0, v97
	s_nop 0
	v_lshl_add_u32 v0, v8, 7, v10
	v_add_u32_e32 v8, s38, v8
	ds_read_b128 v[0:3], v0
	v_mad_i64_i32 v[6:7], s[16:17], v8, s15, v[6:7]
	v_lshl_add_u64 v[6:7], v[6:7], 0, s[0:1]
	v_readlane_b32 s0, v218, 38
	s_add_i32 s5, s5, s0
	v_readlane_b32 s0, v218, 31
	s_add_i32 s4, s4, s0
	v_readlane_b32 s0, v221, 7
	v_lshl_add_u64 v[4:5], v[6:7], 0, v[4:5]
	s_cmp_lt_i32 s5, s0
	s_waitcnt lgkmcnt(0)
	global_store_dwordx4 v[4:5], v[0:3], off sc0 sc1
	s_barrier
	s_cbranch_scc0 .LBB0_198

; DI float silu_f(float x) { return x * __builtin_amdgcn_rcpf(1.f + __expf(-x)); }
; template <int EPI, int MI>
; DI void gemm_tile(const GemmDesc& g, int tm, int tn, char* smem) {
;     ...
;   if (EPI == EPI_SWIGLU) {
;     u16* es = (u16*)smem;
; #pragma unroll
;     for (int mi = 0; mi < MI; ++mi)
; #pragma unroll
;       for (int i = 0; i < 16; ++i) {
;         const int lrow = wm * (32 * MI) + mi * 32 + (i & 3) + 8 * (i >> 2) + 4 * hh;
;         es[lrow * 64 + wn * 32 + r] = f2bf(silu_f(acc[mi][0][i]) * acc[mi][1][i]);
.LBB0_1420:
	s_nop 7
	v_mul_f32_e32 v162, 0xbfb8aa3b, v80
	v_mul_f32_e32 v163, 0xbfb8aa3b, v81
	v_mul_f32_e32 v164, 0xbfb8aa3b, v82
	v_mul_f32_e32 v165, 0xbfb8aa3b, v83
	v_mul_f32_e32 v166, 0xbfb8aa3b, v84
	v_mul_f32_e32 v167, 0xbfb8aa3b, v85
	v_mul_f32_e32 v168, 0xbfb8aa3b, v86
	v_mul_f32_e32 v169, 0xbfb8aa3b, v87
	v_mul_f32_e32 v170, 0xbfb8aa3b, v88
	v_mul_f32_e32 v171, 0xbfb8aa3b, v89
	v_mul_f32_e32 v172, 0xbfb8aa3b, v90
	v_mul_f32_e32 v173, 0xbfb8aa3b, v91
	v_mul_f32_e32 v174, 0xbfb8aa3b, v92
	v_mul_f32_e32 v175, 0xbfb8aa3b, v93
	v_mul_f32_e32 v176, 0xbfb8aa3b, v94
	v_mul_f32_e32 v177, 0xbfb8aa3b, v95
	v_exp_f32_e32 v162, v162
	v_exp_f32_e32 v163, v163
	v_exp_f32_e32 v164, v164
	v_exp_f32_e32 v165, v165
	v_exp_f32_e32 v166, v166
	v_exp_f32_e32 v167, v167
	v_exp_f32_e32 v168, v168
	v_exp_f32_e32 v169, v169
	v_exp_f32_e32 v170, v170
	v_exp_f32_e32 v171, v171
	v_exp_f32_e32 v172, v172
	v_exp_f32_e32 v173, v173
	v_exp_f32_e32 v174, v174
	v_exp_f32_e32 v175, v175
	v_exp_f32_e32 v176, v176
	v_exp_f32_e32 v177, v177
	v_add_f32_e32 v162, 1.0, v162
	v_add_f32_e32 v163, 1.0, v163
	v_add_f32_e32 v164, 1.0, v164
	v_add_f32_e32 v165, 1.0, v165
	v_add_f32_e32 v166, 1.0, v166
	v_add_f32_e32 v167, 1.0, v167
	v_add_f32_e32 v168, 1.0, v168
	v_add_f32_e32 v169, 1.0, v169
	v_add_f32_e32 v170, 1.0, v170
	v_add_f32_e32 v171, 1.0, v171
	v_add_f32_e32 v172, 1.0, v172
	v_add_f32_e32 v173, 1.0, v173
	v_add_f32_e32 v174, 1.0, v174
	v_add_f32_e32 v175, 1.0, v175
	v_add_f32_e32 v176, 1.0, v176
	v_add_f32_e32 v177, 1.0, v177
	v_rcp_f32_e32 v162, v162
	v_rcp_f32_e32 v163, v163
	v_rcp_f32_e32 v164, v164
	v_rcp_f32_e32 v165, v165
	v_rcp_f32_e32 v166, v166
	v_rcp_f32_e32 v167, v167
	v_rcp_f32_e32 v168, v168
	v_rcp_f32_e32 v169, v169
	v_rcp_f32_e32 v170, v170
	v_rcp_f32_e32 v171, v171
	v_rcp_f32_e32 v172, v172
	v_rcp_f32_e32 v173, v173
	v_rcp_f32_e32 v174, v174
	v_rcp_f32_e32 v175, v175
	v_rcp_f32_e32 v176, v176
	v_rcp_f32_e32 v177, v177
	v_mul_f32_e32 v80, v80, v162
	v_mul_f32_e32 v81, v81, v163
	v_mul_f32_e32 v82, v82, v164
	v_mul_f32_e32 v83, v83, v165
	v_mul_f32_e32 v84, v84, v166
	v_mul_f32_e32 v85, v85, v167
	v_mul_f32_e32 v86, v86, v168
	v_mul_f32_e32 v87, v87, v169
	v_mul_f32_e32 v88, v88, v170
	v_mul_f32_e32 v89, v89, v171
	v_mul_f32_e32 v90, v90, v172
	v_mul_f32_e32 v91, v91, v173
	v_mul_f32_e32 v92, v92, v174
	v_mul_f32_e32 v93, v93, v175
	v_mul_f32_e32 v94, v94, v176
	v_mul_f32_e32 v95, v95, v177
	v_mul_f32_e32 v80, v64, v80
	v_mul_f32_e32 v81, v65, v81
	v_mul_f32_e32 v82, v66, v82
	v_mul_f32_e32 v83, v67, v83
	v_mul_f32_e32 v84, v68, v84
	v_mul_f32_e32 v85, v69, v85
	v_mul_f32_e32 v86, v70, v86
	v_mul_f32_e32 v87, v71, v87
	v_mul_f32_e32 v88, v72, v88
	v_mul_f32_e32 v89, v73, v89
	v_mul_f32_e32 v90, v74, v90
	v_mul_f32_e32 v91, v75, v91
	v_mul_f32_e32 v92, v76, v92
	v_mul_f32_e32 v93, v77, v93
	v_mul_f32_e32 v94, v78, v94
	v_mul_f32_e32 v95, v79, v95
	v_cvt_pk_bf16_f32 v80, v80, s0
	v_cvt_pk_bf16_f32 v81, v81, s0
	v_cvt_pk_bf16_f32 v82, v82, s0
	v_cvt_pk_bf16_f32 v83, v83, s0
	v_cvt_pk_bf16_f32 v84, v84, s0
	v_cvt_pk_bf16_f32 v85, v85, s0
	v_cvt_pk_bf16_f32 v86, v86, s0
	v_cvt_pk_bf16_f32 v87, v87, s0
	v_cvt_pk_bf16_f32 v88, v88, s0
	v_cvt_pk_bf16_f32 v89, v89, s0
	v_cvt_pk_bf16_f32 v90, v90, s0
	v_cvt_pk_bf16_f32 v91, v91, s0
	v_cvt_pk_bf16_f32 v92, v92, s0
	v_cvt_pk_bf16_f32 v93, v93, s0
	v_cvt_pk_bf16_f32 v94, v94, s0
	v_cvt_pk_bf16_f32 v95, v95, s0
	v_mul_f32_e32 v162, 0xbfb8aa3b, v48
	v_mul_f32_e32 v163, 0xbfb8aa3b, v49
	v_mul_f32_e32 v164, 0xbfb8aa3b, v50
	v_mul_f32_e32 v165, 0xbfb8aa3b, v51
	v_mul_f32_e32 v166, 0xbfb8aa3b, v52
	v_mul_f32_e32 v167, 0xbfb8aa3b, v53
	v_mul_f32_e32 v168, 0xbfb8aa3b, v54
	v_mul_f32_e32 v169, 0xbfb8aa3b, v55
	v_mul_f32_e32 v170, 0xbfb8aa3b, v56
	v_mul_f32_e32 v171, 0xbfb8aa3b, v57
	v_mul_f32_e32 v172, 0xbfb8aa3b, v58
	v_mul_f32_e32 v173, 0xbfb8aa3b, v59
	v_mul_f32_e32 v174, 0xbfb8aa3b, v60
	v_mul_f32_e32 v175, 0xbfb8aa3b, v61
	v_mul_f32_e32 v176, 0xbfb8aa3b, v62
	v_mul_f32_e32 v177, 0xbfb8aa3b, v63
	v_exp_f32_e32 v162, v162
	v_exp_f32_e32 v163, v163
	v_exp_f32_e32 v164, v164
	v_exp_f32_e32 v165, v165
	v_exp_f32_e32 v166, v166
	v_exp_f32_e32 v167, v167
	v_exp_f32_e32 v168, v168
	v_exp_f32_e32 v169, v169
	v_exp_f32_e32 v170, v170
	v_exp_f32_e32 v171, v171
	v_exp_f32_e32 v172, v172
	v_exp_f32_e32 v173, v173
	v_exp_f32_e32 v174, v174
	v_exp_f32_e32 v175, v175
	v_exp_f32_e32 v176, v176
	v_exp_f32_e32 v177, v177
	v_add_f32_e32 v162, 1.0, v162
	v_add_f32_e32 v163, 1.0, v163
	v_add_f32_e32 v164, 1.0, v164
	v_add_f32_e32 v165, 1.0, v165
	v_add_f32_e32 v166, 1.0, v166
	v_add_f32_e32 v167, 1.0, v167
	v_add_f32_e32 v168, 1.0, v168
	v_add_f32_e32 v169, 1.0, v169
	v_add_f32_e32 v170, 1.0, v170
	v_add_f32_e32 v171, 1.0, v171
	v_add_f32_e32 v172, 1.0, v172
	v_add_f32_e32 v173, 1.0, v173
	v_add_f32_e32 v174, 1.0, v174
	v_add_f32_e32 v175, 1.0, v175
	v_add_f32_e32 v176, 1.0, v176
	v_add_f32_e32 v177, 1.0, v177
	v_rcp_f32_e32 v162, v162
	v_rcp_f32_e32 v163, v163
	v_rcp_f32_e32 v164, v164
	v_rcp_f32_e32 v165, v165
	v_rcp_f32_e32 v166, v166
	v_rcp_f32_e32 v167, v167
	v_rcp_f32_e32 v168, v168
	v_rcp_f32_e32 v169, v169
	v_rcp_f32_e32 v170, v170
	v_rcp_f32_e32 v171, v171
	v_rcp_f32_e32 v172, v172
	v_rcp_f32_e32 v173, v173
	v_rcp_f32_e32 v174, v174
	v_rcp_f32_e32 v175, v175
	v_rcp_f32_e32 v176, v176
	v_rcp_f32_e32 v177, v177
	v_mul_f32_e32 v48, v48, v162
	v_mul_f32_e32 v49, v49, v163
	v_mul_f32_e32 v50, v50, v164
	v_mul_f32_e32 v51, v51, v165
	v_mul_f32_e32 v52, v52, v166
	v_mul_f32_e32 v53, v53, v167
	v_mul_f32_e32 v54, v54, v168
	v_mul_f32_e32 v55, v55, v169
	v_mul_f32_e32 v56, v56, v170
	v_mul_f32_e32 v57, v57, v171
	v_mul_f32_e32 v58, v58, v172
; DI float silu_f(float x) { return x * __builtin_amdgcn_rcpf(1.f + __expf(-x)); }
; template <int EPI, int MI>
; DI void gemm_tile(const GemmDesc& g, int tm, int tn, char* smem) {
;     ...
; #pragma unroll
;     for (int mi = 0; mi < MI; ++mi)
; #pragma unroll
;       for (int i = 0; i < 16; ++i) {
;         const int lrow = wm * (32 * MI) + mi * 32 + (i & 3) + 8 * (i >> 2) + 4 * hh;
;         es[lrow * 64 + wn * 32 + r] = f2bf(silu_f(acc[mi][0][i]) * acc[mi][1][i]);
;       }
;     __syncthreads();
	v_mul_f32_e32 v59, v59, v173
	v_mul_f32_e32 v60, v60, v174
	v_mul_f32_e32 v61, v61, v175
	v_mul_f32_e32 v62, v62, v176
	v_mul_f32_e32 v63, v63, v177
	v_mul_f32_e32 v48, v32, v48
	v_mul_f32_e32 v49, v33, v49
	v_mul_f32_e32 v50, v34, v50
	v_mul_f32_e32 v51, v35, v51
	v_mul_f32_e32 v52, v36, v52
	v_mul_f32_e32 v53, v37, v53
	v_mul_f32_e32 v54, v38, v54
	v_mul_f32_e32 v55, v39, v55
	v_mul_f32_e32 v56, v40, v56
	v_mul_f32_e32 v57, v41, v57
	v_mul_f32_e32 v58, v42, v58
	v_mul_f32_e32 v59, v43, v59
	v_mul_f32_e32 v60, v44, v60
	v_mul_f32_e32 v61, v45, v61
	v_mul_f32_e32 v62, v46, v62
	v_mul_f32_e32 v63, v47, v63
	v_cvt_pk_bf16_f32 v48, v48, s0
	v_cvt_pk_bf16_f32 v49, v49, s0
	v_cvt_pk_bf16_f32 v50, v50, s0
	v_cvt_pk_bf16_f32 v51, v51, s0
	v_cvt_pk_bf16_f32 v52, v52, s0
	v_cvt_pk_bf16_f32 v53, v53, s0
	v_cvt_pk_bf16_f32 v54, v54, s0
	v_cvt_pk_bf16_f32 v55, v55, s0
	v_cvt_pk_bf16_f32 v56, v56, s0
	v_cvt_pk_bf16_f32 v57, v57, s0
	v_cvt_pk_bf16_f32 v58, v58, s0
	v_cvt_pk_bf16_f32 v59, v59, s0
	v_cvt_pk_bf16_f32 v60, v60, s0
	v_cvt_pk_bf16_f32 v61, v61, s0
	v_cvt_pk_bf16_f32 v62, v62, s0
	v_cvt_pk_bf16_f32 v63, v63, s0
	v_mul_f32_e32 v162, 0xbfb8aa3b, v16
	v_mul_f32_e32 v163, 0xbfb8aa3b, v17
	v_mul_f32_e32 v164, 0xbfb8aa3b, v18
	v_mul_f32_e32 v165, 0xbfb8aa3b, v19
	v_mul_f32_e32 v166, 0xbfb8aa3b, v20
	v_mul_f32_e32 v167, 0xbfb8aa3b, v21
	v_mul_f32_e32 v168, 0xbfb8aa3b, v22
	v_mul_f32_e32 v169, 0xbfb8aa3b, v23
	v_mul_f32_e32 v170, 0xbfb8aa3b, v24
	v_mul_f32_e32 v171, 0xbfb8aa3b, v25
	v_mul_f32_e32 v172, 0xbfb8aa3b, v26
	v_mul_f32_e32 v173, 0xbfb8aa3b, v27
	v_mul_f32_e32 v174, 0xbfb8aa3b, v28
	v_mul_f32_e32 v175, 0xbfb8aa3b, v29
	v_mul_f32_e32 v176, 0xbfb8aa3b, v30
	v_mul_f32_e32 v177, 0xbfb8aa3b, v31
	v_exp_f32_e32 v162, v162
	v_exp_f32_e32 v163, v163
	v_exp_f32_e32 v164, v164
	v_exp_f32_e32 v165, v165
	v_exp_f32_e32 v166, v166
	v_exp_f32_e32 v167, v167
	v_exp_f32_e32 v168, v168
	v_exp_f32_e32 v169, v169
	v_exp_f32_e32 v170, v170
	v_exp_f32_e32 v171, v171
	v_exp_f32_e32 v172, v172
	v_exp_f32_e32 v173, v173
	v_exp_f32_e32 v174, v174
	v_exp_f32_e32 v175, v175
	v_exp_f32_e32 v176, v176
	v_exp_f32_e32 v177, v177
	v_add_f32_e32 v162, 1.0, v162
	v_add_f32_e32 v163, 1.0, v163
	v_add_f32_e32 v164, 1.0, v164
	v_add_f32_e32 v165, 1.0, v165
	v_add_f32_e32 v166, 1.0, v166
	v_add_f32_e32 v167, 1.0, v167
	v_add_f32_e32 v168, 1.0, v168
	v_add_f32_e32 v169, 1.0, v169
	v_add_f32_e32 v170, 1.0, v170
	v_add_f32_e32 v171, 1.0, v171
	v_add_f32_e32 v172, 1.0, v172
	v_add_f32_e32 v173, 1.0, v173
	v_add_f32_e32 v174, 1.0, v174
	v_add_f32_e32 v175, 1.0, v175
	v_add_f32_e32 v176, 1.0, v176
	v_add_f32_e32 v177, 1.0, v177
	v_rcp_f32_e32 v162, v162
	v_rcp_f32_e32 v163, v163
	v_rcp_f32_e32 v164, v164
	v_rcp_f32_e32 v165, v165
	v_rcp_f32_e32 v166, v166
	v_rcp_f32_e32 v167, v167
	v_rcp_f32_e32 v168, v168
	v_rcp_f32_e32 v169, v169
	v_rcp_f32_e32 v170, v170
	v_rcp_f32_e32 v171, v171
	v_rcp_f32_e32 v172, v172
	v_rcp_f32_e32 v173, v173
	v_rcp_f32_e32 v174, v174
	v_rcp_f32_e32 v175, v175
	v_rcp_f32_e32 v176, v176
	v_rcp_f32_e32 v177, v177
	v_mul_f32_e32 v16, v16, v162
	v_mul_f32_e32 v17, v17, v163
	v_mul_f32_e32 v18, v18, v164
	v_mul_f32_e32 v19, v19, v165
	v_mul_f32_e32 v20, v20, v166
	v_mul_f32_e32 v21, v21, v167
	v_mul_f32_e32 v22, v22, v168
	v_mul_f32_e32 v23, v23, v169
	v_mul_f32_e32 v24, v24, v170
	v_mul_f32_e32 v25, v25, v171
	v_mul_f32_e32 v26, v26, v172
	v_mul_f32_e32 v27, v27, v173
	v_mul_f32_e32 v28, v28, v174
	v_mul_f32_e32 v29, v29, v175
	v_mul_f32_e32 v30, v30, v176
	v_mul_f32_e32 v31, v31, v177
	v_mul_f32_e32 v16, v0, v16
	v_mul_f32_e32 v17, v1, v17
	v_mul_f32_e32 v18, v2, v18
	v_mul_f32_e32 v19, v3, v19
	v_mul_f32_e32 v20, v4, v20
	v_mul_f32_e32 v21, v5, v21
	v_mul_f32_e32 v22, v6, v22
	v_mul_f32_e32 v23, v7, v23
	v_mul_f32_e32 v24, v8, v24
	v_mul_f32_e32 v25, v9, v25
	v_mul_f32_e32 v26, v10, v26
	v_mul_f32_e32 v27, v11, v27
	v_mul_f32_e32 v28, v12, v28
	v_mul_f32_e32 v29, v13, v29
	v_mul_f32_e32 v30, v14, v30
	v_mul_f32_e32 v31, v15, v31
	v_cvt_pk_bf16_f32 v16, v16, s0
	v_cvt_pk_bf16_f32 v17, v17, s0
	v_cvt_pk_bf16_f32 v18, v18, s0
	v_cvt_pk_bf16_f32 v19, v19, s0
	v_cvt_pk_bf16_f32 v20, v20, s0
	v_cvt_pk_bf16_f32 v21, v21, s0
	v_cvt_pk_bf16_f32 v22, v22, s0
	v_cvt_pk_bf16_f32 v23, v23, s0
	v_cvt_pk_bf16_f32 v24, v24, s0
	v_cvt_pk_bf16_f32 v25, v25, s0
	v_cvt_pk_bf16_f32 v26, v26, s0
	v_cvt_pk_bf16_f32 v27, v27, s0
	v_cvt_pk_bf16_f32 v28, v28, s0
	v_cvt_pk_bf16_f32 v29, v29, s0
	v_cvt_pk_bf16_f32 v30, v30, s0
	v_cvt_pk_bf16_f32 v31, v31, s0
	v_lshlrev_b32_e32 v99, 9, v122
	v_lshlrev_b32_e32 v100, 6, v123
	v_add3_u32 v99, 0, v99, v100
	v_lshlrev_b32_e32 v100, 1, v121
	v_readlane_b32 s16, v221, 5
	v_readlane_b32 s17, v221, 6
	s_movk_i32 s0, 0x3000
	v_mul_lo_u32 v64, v120, s0
	v_add3_u32 v64, v99, v100, v64
	s_movk_i32 s15, 0x1600
	v_lshlrev_b32_e32 v4, 4, v115
	v_mov_b32_e32 v5, v96
	v_mov_b64_e32 v[6:7], s[16:17]
	v_mad_i64_i32 v[8:9], s[16:17], v98, s15, v[6:7]
	v_add_u32_e32 v10, 0, v4
	v_lshl_add_u32 v0, v97, 7, v10
	ds_write_b16 v64, v80
	ds_write_b16 v64, v81 offset:128
	ds_write_b16 v64, v82 offset:256
	ds_write_b16 v64, v83 offset:384
	ds_write_b16 v64, v84 offset:1024
	ds_write_b16 v64, v85 offset:1152
	ds_write_b16 v64, v86 offset:1280
	ds_write_b16 v64, v87 offset:1408
	ds_write_b16 v64, v88 offset:2048
	ds_write_b16 v64, v89 offset:2176
	ds_write_b16 v64, v90 offset:2304
	ds_write_b16 v64, v91 offset:2432
	ds_write_b16 v64, v92 offset:3072
	ds_write_b16 v64, v93 offset:3200
	ds_write_b16 v64, v94 offset:3328
	ds_write_b16 v64, v95 offset:3456
	ds_write_b16 v64, v48 offset:4096
	ds_write_b16 v64, v49 offset:4224
	ds_write_b16 v64, v50 offset:4352
	ds_write_b16 v64, v51 offset:4480
	ds_write_b16 v64, v52 offset:5120
	ds_write_b16 v64, v53 offset:5248
	ds_write_b16 v64, v54 offset:5376
	ds_write_b16 v64, v55 offset:5504
	ds_write_b16 v64, v56 offset:6144
	ds_write_b16 v64, v57 offset:6272
	ds_write_b16 v64, v58 offset:6400
	ds_write_b16 v64, v59 offset:6528
	ds_write_b16 v64, v60 offset:7168
	ds_write_b16 v64, v61 offset:7296
	ds_write_b16 v64, v62 offset:7424
	ds_write_b16 v64, v63 offset:7552
	ds_write_b16 v64, v16 offset:8192
	ds_write_b16 v64, v17 offset:8320
	ds_write_b16 v64, v18 offset:8448
	ds_write_b16 v64, v19 offset:8576
	ds_write_b16 v64, v20 offset:9216
	ds_write_b16 v64, v21 offset:9344
	ds_write_b16 v64, v22 offset:9472
	ds_write_b16 v64, v23 offset:9600
	ds_write_b16 v64, v24 offset:10240
	ds_write_b16 v64, v25 offset:10368
	ds_write_b16 v64, v26 offset:10496
	ds_write_b16 v64, v27 offset:10624
	ds_write_b16 v64, v28 offset:11264
	ds_write_b16 v64, v29 offset:11392
	ds_write_b16 v64, v30 offset:11520
	ds_write_b16 v64, v31 offset:11648
	s_waitcnt lgkmcnt(0)
	s_barrier
; template <int EPI, int MI>
; DI void gemm_tile(const GemmDesc& g, int tm, int tn, char* smem) {
;     ...
; #pragma unroll
;     for (int j = 0; j < 2 * MI; ++j) {
;       const int lrow = (tid >> 3) + 32 * j, ch = tid & 7;
;       const u32x4 v = *(const u32x4*)(es + lrow * 64 + ch * 8);
;       *(u32x4*)(g.o16 + (size_t)(m0 + lrow) * g.ldo + (n0 >> 1) + ch * 8) = v;
;     }
;     __syncthreads();
; template <int EPI, int MI>
; DI void gemm_phase(const GemmDesc& g, char* smem, int vb, int nvb) {
;     ...
;   for (int q = start; q < local; q += step) {
	s_lshl_b32 s0, s39, 6
	ds_read_b128 v[0:3], v0
	s_ashr_i32 s1, s0, 31
	s_lshl_b64 s[0:1], s[0:1], 1
	v_lshl_add_u64 v[8:9], v[8:9], 0, s[0:1]
	v_lshl_add_u64 v[8:9], v[8:9], 0, v[4:5]
	s_waitcnt lgkmcnt(0)
	global_store_dwordx4 v[8:9], v[0:3], off sc0 sc1
	v_add_u32_e32 v8, 32, v97
	s_nop 0
	v_lshl_add_u32 v0, v8, 7, v10
	ds_read_b128 v[0:3], v0
	v_add_u32_e32 v8, s38, v8
	v_mad_i64_i32 v[8:9], s[16:17], v8, s15, v[6:7]
	v_lshl_add_u64 v[8:9], v[8:9], 0, s[0:1]
	v_lshl_add_u64 v[8:9], v[8:9], 0, v[4:5]
	s_waitcnt lgkmcnt(0)
	global_store_dwordx4 v[8:9], v[0:3], off sc0 sc1
	v_add_u32_e32 v8, 64, v97
	s_nop 0
	v_lshl_add_u32 v0, v8, 7, v10
	ds_read_b128 v[0:3], v0
	v_add_u32_e32 v8, s38, v8
	v_mad_i64_i32 v[8:9], s[16:17], v8, s15, v[6:7]
	v_lshl_add_u64 v[8:9], v[8:9], 0, s[0:1]
	v_lshl_add_u64 v[8:9], v[8:9], 0, v[4:5]
	s_waitcnt lgkmcnt(0)
	global_store_dwordx4 v[8:9], v[0:3], off sc0 sc1
	v_add_u32_e32 v8, 0x60, v97
	s_nop 0
	v_lshl_add_u32 v0, v8, 7, v10
	ds_read_b128 v[0:3], v0
	v_add_u32_e32 v8, s38, v8
	v_mad_i64_i32 v[8:9], s[16:17], v8, s15, v[6:7]
	v_lshl_add_u64 v[8:9], v[8:9], 0, s[0:1]
	v_lshl_add_u64 v[8:9], v[8:9], 0, v[4:5]
	s_waitcnt lgkmcnt(0)
	global_store_dwordx4 v[8:9], v[0:3], off sc0 sc1
	v_add_u32_e32 v8, 0x80, v97
	s_nop 0
	v_lshl_add_u32 v0, v8, 7, v10
	ds_read_b128 v[0:3], v0
	v_add_u32_e32 v8, s38, v8
	v_mad_i64_i32 v[8:9], s[16:17], v8, s15, v[6:7]
	v_lshl_add_u64 v[8:9], v[8:9], 0, s[0:1]
	v_lshl_add_u64 v[8:9], v[8:9], 0, v[4:5]
	s_waitcnt lgkmcnt(0)
	global_store_dwordx4 v[8:9], v[0:3], off sc0 sc1
	v_add_u32_e32 v8, 0xa0, v97
	s_nop 0
	v_lshl_add_u32 v0, v8, 7, v10
	v_add_u32_e32 v8, s38, v8
	ds_read_b128 v[0:3], v0
	v_mad_i64_i32 v[6:7], s[16:17], v8, s15, v[6:7]
	v_lshl_add_u64 v[6:7], v[6:7], 0, s[0:1]
	v_readlane_b32 s0, v218, 38
	s_add_i32 s5, s5, s0
	v_readlane_b32 s0, v218, 31
	s_add_i32 s4, s4, s0
	v_readlane_b32 s0, v221, 7
	v_lshl_add_u64 v[4:5], v[6:7], 0, v[4:5]
	s_cmp_ge_i32 s5, s0
	s_waitcnt lgkmcnt(0)
	global_store_dwordx4 v[4:5], v[0:3], off sc0 sc1
	s_barrier
	s_cbranch_scc1 .LBB0_1417
